# S5 scan loop: 3-deep u prefetch ring, no per-step drain of z stores
# baseline (speedup 1.0000x reference)
.LBB0_349:
	v_lshl_or_b32 v43, s0, 12, v127
	global_load_dwordx4 v[48:51], v43, s[36:37]
	global_load_dwordx4 v[56:59], v43, s[36:37] offset:32
	global_load_dwordx4 v[44:47], v43, s[66:67]
	global_load_dwordx4 v[52:55], v43, s[66:67] offset:32
	global_load_dwordx4 v[60:63], v43, s[66:67] offset:64
	global_load_dwordx4 v[64:67], v43, s[36:37] offset:64
	global_load_dwordx4 v[68:71], v43, s[36:37] offset:96
	s_waitcnt vmcnt(10)
	v_bfe_u32 v36, v27, 16, 1
	v_bfe_u32 v37, v26, 16, 1
	v_bfe_u32 v39, v32, 16, 1
	v_bfe_u32 v41, v30, 16, 1
	v_add3_u32 v30, v30, v41, s15
	v_add3_u32 v32, v32, v39, s15
	v_add3_u32 v26, v26, v37, s15
	v_add3_u32 v27, v27, v36, s15
	s_waitcnt vmcnt(8)
	v_bfe_u32 v36, v19, 16, 1
	v_bfe_u32 v37, v18, 16, 1
	v_bfe_u32 v39, v24, 16, 1
	v_bfe_u32 v41, v22, 16, 1
	v_add3_u32 v22, v22, v41, s15
	v_add3_u32 v24, v24, v39, s15
	v_add3_u32 v18, v18, v37, s15
	v_add3_u32 v19, v19, v36, s15
	v_bfe_u32 v36, v11, 16, 1
	v_bfe_u32 v37, v10, 16, 1
	v_bfe_u32 v39, v16, 16, 1
	v_bfe_u32 v41, v14, 16, 1
	v_add3_u32 v14, v14, v41, s15
	v_add3_u32 v16, v16, v39, s15
	v_add3_u32 v10, v10, v37, s15
	v_add3_u32 v11, v11, v36, s15
	v_bfe_u32 v36, v5, 16, 1
	v_bfe_u32 v37, v3, 16, 1
	v_bfe_u32 v39, v9, 16, 1
	v_bfe_u32 v41, v6, 16, 1
	v_add3_u32 v6, v6, v41, s15
	v_add3_u32 v9, v9, v39, s15
	v_add3_u32 v37, v3, v37, s15
	v_add3_u32 v39, v5, v36, s15
	v_bfe_u32 v35, v28, 16, 1
	v_add3_u32 v28, v28, v35, s15
	v_bfe_u32 v35, v20, 16, 1
	v_add3_u32 v20, v20, v35, s15
	v_bfe_u32 v35, v12, 16, 1
	v_add3_u32 v12, v12, v35, s15
	v_bfe_u32 v35, v2, 16, 1
	v_add3_u32 v35, v2, v35, s15
	v_mul_f32_e32 v2, v141, v141
	v_fma_f32 v156, v140, v140, -v2
	v_add_f32_e32 v2, v140, v140
	v_bfe_u32 v38, v33, 16, 1
	v_mul_f32_e32 v158, v2, v141
	v_bfe_u32 v34, v29, 16, 1
	v_add3_u32 v33, v33, v38, s15
	v_bfe_u32 v38, v25, 16, 1
	v_mul_f32_e32 v2, v141, v158
	v_add3_u32 v29, v29, v34, s15
	v_bfe_u32 v34, v21, 16, 1
	v_add3_u32 v25, v25, v38, s15
	v_bfe_u32 v38, v17, 16, 1
	v_fma_f32 v160, v140, v156, -v2
	v_mul_f32_e32 v2, v158, v158
	v_add3_u32 v21, v21, v34, s15
	s_waitcnt vmcnt(7)
	v_mul_f32_e32 v34, v143, v143
	v_add3_u32 v17, v17, v38, s15
	v_bfe_u32 v38, v4, 16, 1
	v_fma_f32 v164, v156, v156, -v2
	v_add_f32_e32 v2, v156, v156
	v_fma_f32 v144, v142, v142, -v34
	v_add_f32_e32 v34, v142, v142
	v_add3_u32 v38, v4, v38, s15
	v_mul_f32_e32 v166, v158, v2
	v_mul_f32_e32 v146, v34, v143
	v_mul_f32_e32 v34, v143, v146
	v_fma_f32 v148, v142, v144, -v34
	v_mul_f32_e32 v34, v146, v146
	v_bfe_u32 v40, v31, 16, 1
	v_fma_f32 v152, v144, v144, -v34
	v_add_f32_e32 v34, v144, v144
	v_add3_u32 v31, v31, v40, s15
	s_waitcnt vmcnt(6)
	v_xor_b32_e32 v3, 0x80000000, v48
	v_xor_b32_e32 v5, 0x80000000, v49
	v_xor_b32_e32 v36, 0x80000000, v50
	v_xor_b32_e32 v41, 0x80000000, v51
	global_load_dwordx4 v[48:51], v43, s[66:67] offset:96
	v_bfe_u32 v42, v41, 16, 1
	s_waitcnt vmcnt(5)
	v_bfe_u32 v2, v44, 16, 1
	v_bfe_u32 v4, v3, 16, 1
	v_add3_u32 v41, v41, v42, s15
	v_add3_u32 v2, v44, v2, s15
	v_add3_u32 v3, v3, v4, s15
	v_bfe_u32 v4, v45, 16, 1
	v_lshrrev_b32_e32 v41, 16, v41
	v_xor_b32_e32 v44, 0x80000000, v56
	v_add3_u32 v4, v45, v4, s15
	v_cndmask_b32_e64 v42, 0, v41, s[4:5]
	s_waitcnt vmcnt(4)
	v_bfe_u32 v41, v52, 16, 1
	v_bfe_u32 v45, v44, 16, 1
	v_add3_u32 v41, v52, v41, s15
	v_add3_u32 v44, v44, v45, s15
	v_bfe_u32 v45, v53, 16, 1
	v_xor_b32_e32 v52, 0x80000000, v58
	v_add3_u32 v45, v53, v45, s15
	v_bfe_u32 v53, v52, 16, 1
	v_bfe_u32 v40, v23, 16, 1
	v_mul_f32_e32 v154, v146, v34
	v_bfe_u32 v34, v13, 16, 1
	v_add3_u32 v52, v52, v53, s15
	v_add3_u32 v23, v23, v40, s15
	v_bfe_u32 v40, v15, 16, 1
	v_add3_u32 v13, v13, v34, s15
	v_bfe_u32 v34, v8, 16, 1
	v_lshrrev_b32_e32 v52, 16, v52
	v_add3_u32 v15, v15, v40, s15
	v_bfe_u32 v40, v7, 16, 1
	v_add3_u32 v34, v8, v34, s15
	v_bfe_u32 v8, v5, 16, 1
	v_cndmask_b32_e64 v98, 0, v52, s[4:5]
	v_bfe_u32 v52, v55, 16, 1
	v_add3_u32 v7, v7, v40, s15
	v_add3_u32 v5, v5, v8, s15
	v_bfe_u32 v8, v46, 16, 1
	v_bfe_u32 v40, v36, 16, 1
	v_add3_u32 v52, v55, v52, s15
	v_add3_u32 v8, v46, v8, s15
	v_add3_u32 v36, v36, v40, s15
	v_bfe_u32 v40, v47, 16, 1
	v_xor_b32_e32 v46, 0x80000000, v57
	v_lshrrev_b32_e32 v52, 16, v52
	v_add3_u32 v40, v47, v40, s15
	v_bfe_u32 v47, v46, 16, 1
	v_cndmask_b32_e64 v99, 0, v52, s[4:5]
	v_xor_b32_e32 v52, 0x80000000, v59
	v_add3_u32 v46, v46, v47, s15
	v_bfe_u32 v47, v54, 16, 1
	v_bfe_u32 v53, v52, 16, 1
	v_add3_u32 v47, v54, v47, s15
	v_add3_u32 v56, v52, v53, s15
	global_load_dwordx4 v[52:55], v43, s[66:67] offset:128
	v_lshrrev_b32_e32 v56, 16, v56
	v_cndmask_b32_e64 v100, 0, v56, s[4:5]
	global_load_dwordx4 v[56:59], v43, s[36:37] offset:128
	s_waitcnt vmcnt(5)
	v_bfe_u32 v72, v60, 16, 1
	v_add3_u32 v60, v60, v72, s15
	v_lshrrev_b32_e32 v60, 16, v60
	v_cndmask_b32_e64 v102, 0, v60, s[4:5]
	s_waitcnt vmcnt(4)
	v_xor_b32_e32 v60, 0x80000000, v64
	v_bfe_u32 v64, v60, 16, 1
	v_add3_u32 v60, v60, v64, s15
	v_lshrrev_b32_e32 v60, 16, v60
	v_cndmask_b32_e64 v106, 0, v60, s[4:5]
	v_bfe_u32 v60, v61, 16, 1
	v_add3_u32 v60, v61, v60, s15
	v_lshrrev_b32_e32 v60, 16, v60
	v_cndmask_b32_e64 v103, 0, v60, s[4:5]
	v_xor_b32_e32 v60, 0x80000000, v65
	v_bfe_u32 v61, v60, 16, 1
	v_add3_u32 v60, v60, v61, s15
	v_lshrrev_b32_e32 v60, 16, v60
	v_cndmask_b32_e64 v107, 0, v60, s[4:5]
	v_bfe_u32 v60, v62, 16, 1
	v_add3_u32 v60, v62, v60, s15
	v_lshrrev_b32_e32 v60, 16, v60
	v_cndmask_b32_e64 v104, 0, v60, s[4:5]
	v_xor_b32_e32 v60, 0x80000000, v66
	s_waitcnt vmcnt(2)
	v_bfe_u32 v72, v48, 16, 1
	v_bfe_u32 v61, v60, 16, 1
	v_add3_u32 v48, v48, v72, s15
	v_add3_u32 v60, v60, v61, s15
	v_lshrrev_b32_e32 v48, 16, v48
	v_lshrrev_b32_e32 v60, 16, v60
	v_cndmask_b32_e64 v110, 0, v48, s[4:5]
	v_xor_b32_e32 v48, 0x80000000, v68
	v_cndmask_b32_e64 v108, 0, v60, s[4:5]
	v_bfe_u32 v60, v63, 16, 1
	v_bfe_u32 v68, v48, 16, 1
	v_add3_u32 v60, v63, v60, s15
	v_add3_u32 v48, v48, v68, s15
	v_lshrrev_b32_e32 v60, 16, v60
	v_lshrrev_b32_e32 v48, 16, v48
	v_cndmask_b32_e64 v105, 0, v60, s[4:5]
	v_xor_b32_e32 v60, 0x80000000, v67
	v_cndmask_b32_e64 v111, 0, v48, s[4:5]
	v_bfe_u32 v48, v49, 16, 1
	v_bfe_u32 v61, v60, 16, 1
	v_add3_u32 v48, v49, v48, s15
	v_add3_u32 v64, v60, v61, s15
	v_lshrrev_b32_e32 v48, 16, v48
	v_lshrrev_b32_e32 v64, 16, v64
	v_cndmask_b32_e64 v112, 0, v48, s[4:5]
	v_xor_b32_e32 v48, 0x80000000, v69
	global_load_dwordx4 v[60:63], v43, s[66:67] offset:160
	v_cndmask_b32_e64 v109, 0, v64, s[4:5]
	global_load_dwordx4 v[64:67], v43, s[36:37] offset:160
	v_bfe_u32 v49, v48, 16, 1
	v_add3_u32 v48, v48, v49, s15
	v_lshrrev_b32_e32 v48, 16, v48
	v_cndmask_b32_e64 v113, 0, v48, s[4:5]
	v_bfe_u32 v48, v50, 16, 1
	v_add3_u32 v48, v50, v48, s15
	v_lshrrev_b32_e32 v48, 16, v48
	v_cndmask_b32_e64 v114, 0, v48, s[4:5]
	v_xor_b32_e32 v48, 0x80000000, v70
	v_bfe_u32 v49, v48, 16, 1
	v_add3_u32 v48, v48, v49, s15
	v_lshrrev_b32_e32 v48, 16, v48
	v_cndmask_b32_e64 v115, 0, v48, s[4:5]
	v_bfe_u32 v48, v51, 16, 1
	v_add3_u32 v48, v51, v48, s15
	v_lshrrev_b32_e32 v48, 16, v48
	v_cndmask_b32_e64 v116, 0, v48, s[4:5]
	v_xor_b32_e32 v68, 0x80000000, v71
	global_load_dwordx4 v[48:51], v43, s[66:67] offset:192
	v_bfe_u32 v69, v68, 16, 1
	v_add3_u32 v68, v68, v69, s15
	v_lshrrev_b32_e32 v72, 16, v68
	global_load_dwordx4 v[68:71], v43, s[36:37] offset:192
	v_cndmask_b32_e64 v117, 0, v72, s[4:5]
	s_waitcnt vmcnt(5)
	v_bfe_u32 v72, v52, 16, 1
	v_add3_u32 v52, v52, v72, s15
	v_lshrrev_b32_e32 v52, 16, v52
	v_cndmask_b32_e64 v118, 0, v52, s[4:5]
	s_waitcnt vmcnt(4)
	v_xor_b32_e32 v52, 0x80000000, v56
	v_bfe_u32 v56, v52, 16, 1
	v_add3_u32 v52, v52, v56, s15
	v_lshrrev_b32_e32 v52, 16, v52
	v_cndmask_b32_e64 v119, 0, v52, s[4:5]
	v_bfe_u32 v52, v53, 16, 1
	v_add3_u32 v52, v53, v52, s15
	v_lshrrev_b32_e32 v52, 16, v52
	v_cndmask_b32_e64 v120, 0, v52, s[4:5]
	v_xor_b32_e32 v52, 0x80000000, v57
	v_bfe_u32 v53, v52, 16, 1
	v_add3_u32 v52, v52, v53, s15
	v_lshrrev_b32_e32 v52, 16, v52
	v_cndmask_b32_e64 v121, 0, v52, s[4:5]
	v_bfe_u32 v52, v54, 16, 1
	v_add3_u32 v52, v54, v52, s15
	v_lshrrev_b32_e32 v52, 16, v52
	v_cndmask_b32_e64 v122, 0, v52, s[4:5]
	v_xor_b32_e32 v52, 0x80000000, v58
	v_bfe_u32 v53, v52, 16, 1
	v_add3_u32 v52, v52, v53, s15
	v_lshrrev_b32_e32 v52, 16, v52
	v_cndmask_b32_e64 v123, 0, v52, s[4:5]
	v_bfe_u32 v52, v55, 16, 1
	v_add3_u32 v52, v55, v52, s15
	v_lshrrev_b32_e32 v56, 16, v52
	global_load_dwordx4 v[52:55], v43, s[66:67] offset:224
	v_cndmask_b32_e64 v124, 0, v56, s[4:5]
	v_xor_b32_e32 v72, 0x80000000, v59
	global_load_dwordx4 v[56:59], v43, s[36:37] offset:224
	v_bfe_u32 v73, v72, 16, 1
	v_add3_u32 v43, v72, v73, s15
	s_ashr_i32 s8, s58, 6
	s_ashr_i32 s9, s8, 31
	s_and_b32 s1, s41, 63
	s_lshl_b64 s[60:61], s[8:9], 11
	s_lshl_b64 s[8:9], s[8:9], 6
	s_add_u32 s2, s8, 0x10000
	s_addc_u32 s3, s9, 0
	s_and_b64 s[8:9], s[54:55], exec
	s_cselect_b32 s8, s61, s3
	s_cselect_b32 s9, s60, s2
	s_lshl_b32 s44, s0, 5
	v_lshlrev_b32_e32 v130, 1, v128
	v_mul_f32_e32 v150, v143, v144
	v_mul_f32_e32 v162, v141, v156
	v_fmac_f32_e32 v150, v142, v146
	v_fmac_f32_e32 v162, v140, v158
	v_lshrrev_b32_e32 v2, 16, v2
	s_waitcnt vmcnt(5)
	v_bfe_u32 v72, v60, 16, 1
	v_add3_u32 v60, v60, v72, s15
	s_waitcnt vmcnt(4)
	v_xor_b32_e32 v64, 0x80000000, v64
	v_bfe_u32 v72, v64, 16, 1
	v_add3_u32 v64, v64, v72, s15
	v_bfe_u32 v72, v61, 16, 1
	v_xor_b32_e32 v65, 0x80000000, v65
	v_add3_u32 v61, v61, v72, s15
	v_bfe_u32 v72, v65, 16, 1
	v_add3_u32 v65, v65, v72, s15
	v_bfe_u32 v72, v62, 16, 1
	v_xor_b32_e32 v66, 0x80000000, v66
	v_add3_u32 v62, v62, v72, s15
	v_bfe_u32 v72, v66, 16, 1
	v_add3_u32 v66, v66, v72, s15
	v_lshrrev_b32_e32 v66, 16, v66
	v_cndmask_b32_e64 v125, 0, v66, s[4:5]
	v_bfe_u32 v66, v63, 16, 1
	v_add3_u32 v63, v63, v66, s15
	v_xor_b32_e32 v66, 0x80000000, v67
	v_bfe_u32 v67, v66, 16, 1
	v_add3_u32 v66, v66, v67, s15
	v_lshrrev_b32_e32 v66, 16, v66
	v_cndmask_b32_e64 v188, 0, v66, s[4:5]
	s_waitcnt vmcnt(3)
	v_bfe_u32 v66, v48, 16, 1
	v_add3_u32 v48, v48, v66, s15
	v_lshrrev_b32_e32 v48, 16, v48
	v_cndmask_b32_e64 v189, 0, v48, s[4:5]
	s_waitcnt vmcnt(2)
	v_xor_b32_e32 v48, 0x80000000, v68
	v_bfe_u32 v66, v48, 16, 1
	v_add3_u32 v48, v48, v66, s15
	v_lshrrev_b32_e32 v48, 16, v48
	v_cndmask_b32_e64 v190, 0, v48, s[4:5]
	v_bfe_u32 v48, v49, 16, 1
	v_add3_u32 v48, v49, v48, s15
	v_lshrrev_b32_e32 v48, 16, v48
	v_cndmask_b32_e64 v191, 0, v48, s[4:5]
	v_xor_b32_e32 v48, 0x80000000, v69
	v_bfe_u32 v49, v48, 16, 1
	v_add3_u32 v48, v48, v49, s15
	v_lshrrev_b32_e32 v48, 16, v48
	v_cndmask_b32_e64 v192, 0, v48, s[4:5]
	v_bfe_u32 v48, v50, 16, 1
	v_add3_u32 v48, v50, v48, s15
	v_lshrrev_b32_e32 v48, 16, v48
	v_cndmask_b32_e64 v193, 0, v48, s[4:5]
	v_xor_b32_e32 v48, 0x80000000, v70
	v_bfe_u32 v49, v48, 16, 1
	v_add3_u32 v48, v48, v49, s15
	v_lshrrev_b32_e32 v48, 16, v48
	v_cndmask_b32_e64 v194, 0, v48, s[4:5]
	v_bfe_u32 v48, v51, 16, 1
	v_add3_u32 v48, v51, v48, s15
	v_lshrrev_b32_e32 v48, 16, v48
	v_cndmask_b32_e64 v195, 0, v48, s[4:5]
	v_xor_b32_e32 v48, 0x80000000, v71
	v_bfe_u32 v49, v48, 16, 1
	v_add3_u32 v48, v48, v49, s15
	v_lshrrev_b32_e32 v48, 16, v48
	v_cndmask_b32_e64 v196, 0, v48, s[4:5]
	s_waitcnt vmcnt(1)
	v_bfe_u32 v48, v52, 16, 1
	v_add3_u32 v48, v52, v48, s15
	v_lshrrev_b32_e32 v48, 16, v48
	v_cndmask_b32_e64 v52, 0, v48, s[4:5]
	s_waitcnt vmcnt(0)
	v_xor_b32_e32 v48, 0x80000000, v56
	v_bfe_u32 v49, v48, 16, 1
	v_add3_u32 v48, v48, v49, s15
	v_lshrrev_b32_e32 v48, 16, v48
	v_cndmask_b32_e64 v56, 0, v48, s[4:5]
	v_bfe_u32 v48, v53, 16, 1
	v_add3_u32 v48, v53, v48, s15
	v_lshrrev_b32_e32 v48, 16, v48
	v_cndmask_b32_e64 v53, 0, v48, s[4:5]
	v_xor_b32_e32 v48, 0x80000000, v57
	v_bfe_u32 v49, v48, 16, 1
	v_add3_u32 v48, v48, v49, s15
	v_lshrrev_b32_e32 v48, 16, v48
	v_cndmask_b32_e64 v57, 0, v48, s[4:5]
	v_bfe_u32 v48, v54, 16, 1
	v_add3_u32 v48, v54, v48, s15
	v_lshrrev_b32_e32 v48, 16, v48
	v_cndmask_b32_e64 v54, 0, v48, s[4:5]
	v_xor_b32_e32 v48, 0x80000000, v58
	v_bfe_u32 v49, v48, 16, 1
	v_add3_u32 v48, v48, v49, s15
	v_lshrrev_b32_e32 v48, 16, v48
	v_cndmask_b32_e64 v58, 0, v48, s[4:5]
	v_bfe_u32 v48, v55, 16, 1
	v_add3_u32 v48, v55, v48, s15
	v_lshrrev_b32_e32 v48, 16, v48
	v_cndmask_b32_e64 v55, 0, v48, s[4:5]
	v_xor_b32_e32 v48, 0x80000000, v59
	v_bfe_u32 v49, v48, 16, 1
	v_add3_u32 v48, v48, v49, s15
	v_lshrrev_b32_e32 v48, 16, v48
	v_cndmask_b32_e64 v59, 0, v48, s[4:5]
	v_lshlrev_b32_e32 v48, 2, v128
	v_lshl_or_b32 v48, s0, 6, v48
	global_load_dwordx4 v[66:69], v48, s[38:39]
	global_load_dwordx4 v[70:73], v48, s[38:39] offset:32
	v_mov_b32_e32 v49, s8
	v_or_b32_e32 v48, s9, v126
	v_lshlrev_b64 v[48:49], 11, v[48:49]
	v_lshl_add_u64 v[50:51], s[16:17], 0, v[48:49]
	v_lshl_add_u64 v[50:51], v[50:51], 0, s[44:45]
	v_lshl_add_u64 v[50:51], v[50:51], 0, v[130:131]
	global_load_dwordx2 v[90:91], v[50:51], off
	global_load_dwordx2 v[92:93], v[50:51], off offset:16
	v_lshrrev_b32_e32 v3, 16, v3
	v_lshrrev_b32_e32 v4, 16, v4
	v_lshrrev_b32_e32 v5, 16, v5
	v_lshrrev_b32_e32 v8, 16, v8
	v_lshrrev_b32_e32 v36, 16, v36
	v_lshrrev_b32_e32 v40, 16, v40
	v_lshrrev_b32_e32 v41, 16, v41
	v_lshrrev_b32_e32 v44, 16, v44
	v_lshrrev_b32_e32 v45, 16, v45
	v_lshrrev_b32_e32 v46, 16, v46
	v_lshrrev_b32_e32 v47, 16, v47
	v_lshrrev_b32_e32 v43, 16, v43
	v_lshrrev_b32_e32 v60, 16, v60
	v_lshrrev_b32_e32 v64, 16, v64
	v_lshrrev_b32_e32 v61, 16, v61
	v_lshrrev_b32_e32 v65, 16, v65
	v_lshrrev_b32_e32 v62, 16, v62
	v_lshrrev_b32_e32 v63, 16, v63
	v_cndmask_b32_e64 v2, 0, v2, s[4:5]
	v_cndmask_b32_e64 v3, 0, v3, s[4:5]
	v_cndmask_b32_e64 v4, 0, v4, s[4:5]
	v_cndmask_b32_e64 v5, 0, v5, s[4:5]
	v_cndmask_b32_e64 v8, 0, v8, s[4:5]
	v_cndmask_b32_e64 v36, 0, v36, s[4:5]
	v_cndmask_b32_e64 v40, 0, v40, s[4:5]
	v_cndmask_b32_e64 v41, 0, v41, s[4:5]
	v_cndmask_b32_e64 v44, 0, v44, s[4:5]
	v_cndmask_b32_e64 v45, 0, v45, s[4:5]
	v_cndmask_b32_e64 v46, 0, v46, s[4:5]
	v_cndmask_b32_e64 v47, 0, v47, s[4:5]
	v_cndmask_b32_e64 v43, 0, v43, s[4:5]
	v_cndmask_b32_e64 v60, 0, v60, s[4:5]
	v_cndmask_b32_e64 v64, 0, v64, s[4:5]
	v_cndmask_b32_e64 v61, 0, v61, s[4:5]
	v_cndmask_b32_e64 v65, 0, v65, s[4:5]
	v_cndmask_b32_e64 v62, 0, v62, s[4:5]
	v_cndmask_b32_e64 v63, 0, v63, s[4:5]
	v_xor_b32_e32 v170, 0x80000000, v141
	v_xor_b32_e32 v174, 0x80000000, v143
	v_xor_b32_e32 v176, 0x80000000, v166
	v_xor_b32_e32 v178, 0x80000000, v154
	v_xor_b32_e32 v180, 0x80000000, v158
	v_xor_b32_e32 v182, 0x80000000, v146
	v_xor_b32_e32 v184, 0x80000000, v162
	v_xor_b32_e32 v186, 0x80000000, v150
	v_lshl_or_b32 v48, s1, 5, v48
	v_perm_b32 v77, v13, v12, s34
	v_perm_b32 v76, v11, v10, s34
	v_perm_b32 v75, v17, v16, s34
	v_perm_b32 v74, v15, v14, s34
	v_perm_b32 v81, v39, v38, s34
	v_perm_b32 v80, v37, v35, s34
	v_perm_b32 v79, v9, v34, s34
	v_perm_b32 v78, v7, v6, s34
	v_perm_b32 v85, v29, v28, s34
	v_perm_b32 v84, v27, v26, s34
	v_perm_b32 v83, v33, v32, s34
	v_perm_b32 v82, v31, v30, s34
	v_perm_b32 v89, v21, v20, s34
	v_perm_b32 v88, v19, v18, s34
	v_perm_b32 v87, v25, v24, s34
	v_perm_b32 v86, v23, v22, s34
	v_mov_b32_e32 v168, v140
	v_mov_b32_e32 v169, v140
	v_mov_b32_e32 v171, v170
	v_mov_b32_e32 v140, v141
	v_mov_b32_e32 v172, v142
	v_mov_b32_e32 v173, v142
	v_mov_b32_e32 v175, v174
	v_mov_b32_e32 v142, v143
	v_mov_b32_e32 v157, v156
	v_mov_b32_e32 v181, v180
	v_mov_b32_e32 v159, v158
	v_mov_b32_e32 v145, v144
	v_mov_b32_e32 v183, v182
	v_mov_b32_e32 v147, v146
	v_mov_b32_e32 v161, v160
	v_mov_b32_e32 v185, v184
	v_mov_b32_e32 v163, v162
	v_mov_b32_e32 v149, v148
	v_mov_b32_e32 v187, v186
	v_mov_b32_e32 v151, v150
	v_mov_b32_e32 v165, v164
	v_mov_b32_e32 v177, v176
	v_mov_b32_e32 v167, v166
	v_mov_b32_e32 v153, v152
	v_mov_b32_e32 v179, v178
	v_mov_b32_e32 v155, v154
	v_perm_b32 v97, v42, v40, s35
	v_perm_b32 v96, v36, v8, s35
	v_perm_b32 v95, v5, v4, s35
	v_perm_b32 v94, v3, v2, s35
	v_perm_b32 v101, v100, v99, s35
	v_perm_b32 v100, v98, v47, s35
	v_perm_b32 v99, v46, v45, s35
	v_perm_b32 v98, v44, v41, s35
	v_perm_b32 v105, v109, v105, s35
	v_perm_b32 v104, v108, v104, s35
	v_perm_b32 v103, v107, v103, s35
	v_perm_b32 v102, v106, v102, s35
	v_perm_b32 v109, v117, v116, s35
	v_perm_b32 v108, v115, v114, s35
	v_perm_b32 v107, v113, v112, s35
	v_perm_b32 v106, v111, v110, s35
	v_perm_b32 v113, v43, v124, s35
	v_perm_b32 v112, v123, v122, s35
	v_perm_b32 v111, v121, v120, s35
	v_perm_b32 v110, v119, v118, s35
	v_perm_b32 v117, v188, v63, s35
	v_perm_b32 v116, v125, v62, s35
	v_perm_b32 v115, v65, v61, s35
	v_perm_b32 v114, v64, v60, s35
	v_perm_b32 v121, v196, v195, s35
	v_perm_b32 v120, v194, v193, s35
	v_perm_b32 v119, v192, v191, s35
	v_perm_b32 v118, v190, v189, s35
	v_perm_b32 v125, v59, v55, s35
	v_perm_b32 v124, v58, v54, s35
	v_perm_b32 v123, v57, v53, s35
	v_perm_b32 v122, v56, v52, s35
	v_lshl_add_u64 v[188:189], v[136:137], 0, v[48:49]
	s_mov_b32 s98, 0xef810000
	s_mov_b32 s99, -1
	v_lshl_add_u64 v[250:251], v[188:189], 0, s[98:99]
	global_load_dwordx2 v[238:239], v[250:251], off
	global_load_dwordx2 v[240:241], v[250:251], off offset:16
	v_lshl_add_u64 v[250:251], v[250:251], 0, s[56:57]
	global_load_dwordx2 v[242:243], v[250:251], off
	global_load_dwordx2 v[244:245], v[250:251], off offset:16
	v_lshl_add_u64 v[250:251], v[250:251], 0, s[56:57]
	s_waitcnt vmcnt(0)
	s_mov_b32 s99, 0
	s_mov_b32 s0, 0
	s_branch .LBB0_351
.LBB0_350:
	v_mfma_f32_32x32x16_bf16 v[34:49], v[90:93], v[74:77], 0
	s_cmp_eq_u32 s40, s0
	v_mfma_f32_32x32x16_bf16 v[2:17], v[90:93], v[82:85], 0
	s_nop 9
	v_fma_f32 v36, v168, v34, v36
	v_fma_f32 v37, v169, v35, v37
	v_mfma_f32_32x32x16_bf16 v[18:33], v[90:93], v[78:81], 0
	v_fma_f32 v4, v172, v2, v4
	v_fma_f32 v5, v173, v3, v5
	v_mfma_f32_32x32x16_bf16 v[50:65], v[90:93], v[86:89], 0
	s_nop 8
	v_fma_f32 v194, v170, v18, v36
	v_fma_f32 v195, v171, v19, v37
	v_fma_f32 v20, v168, v18, v20
	v_fma_f32 v21, v169, v19, v21
	v_fma_f32 v196, v140, v34, v20
	v_fma_f32 v197, v141, v35, v21
	v_pk_fma_f32 v[36:37], v[174:175], v[50:51], v[4:5]
	v_pk_fma_f32 v[4:5], v[172:173], v[50:51], v[52:53]
	s_nop 0
	v_pk_fma_f32 v[52:53], v[142:143], v[2:3], v[4:5]
	v_pk_fma_f32 v[4:5], v[168:169], v[194:195], v[38:39]
	s_nop 0
	v_pk_fma_f32 v[198:199], v[170:171], v[196:197], v[4:5]
	v_pk_fma_f32 v[4:5], v[168:169], v[196:197], v[22:23]
	s_nop 0
	v_pk_fma_f32 v[200:201], v[140:141], v[194:195], v[4:5]
	v_pk_fma_f32 v[4:5], v[172:173], v[36:37], v[6:7]
	v_pk_fma_f32 v[6:7], v[168:169], v[26:27], v[28:29]
	v_pk_fma_f32 v[38:39], v[174:175], v[52:53], v[4:5]
	v_pk_fma_f32 v[4:5], v[172:173], v[52:53], v[54:55]
	v_pk_fma_f32 v[6:7], v[140:141], v[42:43], v[6:7]
	v_pk_fma_f32 v[54:55], v[142:143], v[36:37], v[4:5]
	v_pk_fma_f32 v[4:5], v[168:169], v[198:199], v[40:41]
	s_nop 0
	v_pk_fma_f32 v[202:203], v[170:171], v[200:201], v[4:5]
	v_pk_fma_f32 v[4:5], v[168:169], v[200:201], v[24:25]
	s_nop 0
	v_pk_fma_f32 v[204:205], v[140:141], v[198:199], v[4:5]
	v_pk_fma_f32 v[4:5], v[172:173], v[38:39], v[8:9]
	v_pk_fma_f32 v[8:9], v[172:173], v[10:11], v[12:13]
	v_pk_fma_f32 v[40:41], v[174:175], v[54:55], v[4:5]
	v_pk_fma_f32 v[4:5], v[172:173], v[54:55], v[56:57]
	v_pk_fma_f32 v[12:13], v[172:173], v[58:59], v[60:61]
	v_pk_fma_f32 v[56:57], v[142:143], v[38:39], v[4:5]
	v_pk_fma_f32 v[4:5], v[168:169], v[42:43], v[44:45]
	v_pk_fma_f32 v[8:9], v[174:175], v[58:59], v[8:9]
	v_pk_fma_f32 v[4:5], v[170:171], v[26:27], v[4:5]
	v_pk_fma_f32 v[12:13], v[142:143], v[10:11], v[12:13]
	v_mov_b32_e32 v130, v204
	v_pk_fma_f32 v[20:21], v[168:169], v[4:5], v[46:47]
	v_pk_fma_f32 v[22:23], v[168:169], v[6:7], v[30:31]
	v_pk_fma_f32 v[20:21], v[170:171], v[6:7], v[20:21]
	v_pk_fma_f32 v[14:15], v[172:173], v[8:9], v[14:15]
	v_pk_fma_f32 v[24:25], v[172:173], v[12:13], v[62:63]
	v_mov_b32_e32 v46, v202
	v_mov_b32_e32 v47, v202
	v_pk_fma_f32 v[22:23], v[140:141], v[4:5], v[22:23]
	v_pk_fma_f32 v[14:15], v[174:175], v[12:13], v[14:15]
	v_pk_fma_f32 v[24:25], v[142:143], v[8:9], v[24:25]
	v_pk_fma_f32 v[28:29], v[168:169], v[20:21], v[48:49]
	v_permlane32_swap_b32_e32 v46, v47
	v_mov_b32_e32 v49, v204
	s_nop 1
	v_permlane32_swap_b32_e32 v49, v130
	v_pk_fma_f32 v[30:31], v[168:169], v[22:23], v[32:33]
	v_pk_fma_f32 v[16:17], v[172:173], v[14:15], v[16:17]
	v_pk_fma_f32 v[32:33], v[172:173], v[24:25], v[64:65]
	v_mov_b32_e32 v48, v203
	v_mov_b32_e32 v212, v203
	v_mov_b32_e32 v63, v40
	v_mov_b32_e32 v219, v40
	v_mov_b32_e32 v220, v56
	v_mov_b32_e32 v221, v56
	v_fmac_f32_e32 v46, v164, v211
	v_pk_fma_f32 v[28:29], v[170:171], v[22:23], v[28:29]
	v_pk_fma_f32 v[30:31], v[140:141], v[20:21], v[30:31]
	v_pk_fma_f32 v[16:17], v[174:175], v[24:25], v[16:17]
	v_pk_fma_f32 v[32:33], v[142:143], v[14:15], v[32:33]
	v_permlane32_swap_b32_e32 v48, v212
	v_mov_b32_e32 v213, v205
	v_mov_b32_e32 v214, v205
	v_permlane32_swap_b32_e32 v63, v219
	v_permlane32_swap_b32_e32 v220, v221
	v_fma_f32 v231, -v166, v210, v46
	v_fmac_f32_e32 v49, v164, v210
	v_permlane32_swap_b32_e32 v213, v214
	v_mov_b32_e32 v60, v28
	v_mov_b32_e32 v215, v28
	v_mov_b32_e32 v64, v41
	v_mov_b32_e32 v222, v41
	v_mov_b32_e32 v223, v57
	v_mov_b32_e32 v224, v57
	v_fmac_f32_e32 v49, v166, v211
	v_fmac_f32_e32 v63, v152, v208
	v_fmac_f32_e32 v220, v152, v209
	v_fmac_f32_e32 v48, v164, v231
	v_permlane32_swap_b32_e32 v60, v215
	v_mov_b32_e32 v216, v30
	v_mov_b32_e32 v217, v30
	v_permlane32_swap_b32_e32 v64, v222
	v_permlane32_swap_b32_e32 v223, v224
	v_fma_f32 v232, -v154, v209, v63
	v_fmac_f32_e32 v220, v154, v208
	v_fma_f32 v233, -v166, v49, v48
	v_fmac_f32_e32 v213, v164, v49
	v_permlane32_swap_b32_e32 v216, v217
	v_mov_b32_e32 v61, v29
	v_mov_b32_e32 v218, v29
	v_mov_b32_e32 v65, v16
	v_mov_b32_e32 v225, v16
	v_mov_b32_e32 v226, v32
	v_mov_b32_e32 v227, v32
	v_fmac_f32_e32 v213, v166, v231
	v_fmac_f32_e32 v64, v152, v232
	v_fmac_f32_e32 v223, v152, v220
	v_fmac_f32_e32 v60, v164, v233
	v_permlane32_swap_b32_e32 v61, v218
	v_mov_b32_e32 v62, v31
	v_mov_b32_e32 v44, v31
	v_permlane32_swap_b32_e32 v65, v225
	v_permlane32_swap_b32_e32 v226, v227
	v_fma_f32 v234, -v154, v220, v64
	v_fmac_f32_e32 v223, v154, v232
	v_fma_f32 v235, -v166, v213, v60
	v_fmac_f32_e32 v216, v164, v213
	v_permlane32_swap_b32_e32 v62, v44
	v_mov_b32_e32 v228, v17
	v_mov_b32_e32 v229, v17
	v_mov_b32_e32 v230, v33
	v_mov_b32_e32 v45, v33
	v_fmac_f32_e32 v216, v166, v233
	v_fmac_f32_e32 v65, v152, v234
	v_fmac_f32_e32 v226, v152, v223
	v_fmac_f32_e32 v61, v164, v235
	v_permlane32_swap_b32_e32 v228, v229
	v_permlane32_swap_b32_e32 v230, v45
	v_fma_f32 v236, -v154, v223, v65
	v_fmac_f32_e32 v226, v154, v234
	v_fma_f32 v46, -v166, v216, v61
	v_fmac_f32_e32 v62, v164, v216
	v_fmac_f32_e32 v62, v166, v235
	v_fmac_f32_e32 v228, v152, v236
	v_fmac_f32_e32 v230, v152, v226
	v_fmac_f32_e32 v47, v164, v46
	v_fma_f32 v228, -v154, v226, v228
	v_fmac_f32_e32 v230, v154, v236
	v_fma_f32 v237, -v166, v62, v47
	v_fmac_f32_e32 v130, v164, v62
	v_fmac_f32_e32 v130, v166, v46
	v_cndmask_b32_e64 v46, v46, v211, s[6:7]
	v_cndmask_b32_e64 v47, v237, v231, s[6:7]
	v_cndmask_b32_e64 v48, v62, v210, s[6:7]
	v_cndmask_b32_e64 v49, v130, v49, s[6:7]
	v_pk_fma_f32 v[34:35], v[168:169], v[46:47], v[34:35]
	v_fmac_f32_e32 v219, v152, v228
	v_pk_fma_f32 v[60:61], v[170:171], v[48:49], v[34:35]
	v_pk_fma_f32 v[34:35], v[156:157], v[46:47], v[194:195]
	v_fmac_f32_e32 v221, v152, v230
	v_pk_fma_f32 v[62:63], v[180:181], v[48:49], v[34:35]
	v_pk_fma_f32 v[34:35], v[156:157], v[48:49], v[196:197]
	v_pk_fma_f32 v[64:65], v[160:161], v[46:47], v[198:199]
	v_pk_fma_f32 v[194:195], v[160:161], v[48:49], v[200:201]
	v_pk_fma_f32 v[196:197], v[164:165], v[46:47], v[202:203]
	v_pk_fma_f32 v[198:199], v[164:165], v[48:49], v[204:205]
	v_pk_fma_f32 v[18:19], v[168:169], v[48:49], v[18:19]
	v_fma_f32 v200, -v154, v230, v219
	v_fmac_f32_e32 v221, v154, v228
	v_pk_fma_f32 v[64:65], v[184:185], v[48:49], v[64:65]
	v_pk_fma_f32 v[196:197], v[176:177], v[48:49], v[196:197]
	v_pk_fma_f32 v[18:19], v[140:141], v[46:47], v[18:19]
	v_pk_fma_f32 v[48:49], v[158:159], v[46:47], v[34:35]
	v_pk_fma_f32 v[194:195], v[162:163], v[46:47], v[194:195]
	v_pk_fma_f32 v[46:47], v[166:167], v[46:47], v[198:199]
	v_cndmask_b32_e64 v198, v230, v209, s[6:7]
	v_cndmask_b32_e64 v199, v221, v220, s[6:7]
	v_cndmask_b32_e64 v34, v228, v208, s[6:7]
	v_cndmask_b32_e64 v35, v200, v232, s[6:7]
	v_pk_fma_f32 v[52:53], v[144:145], v[198:199], v[52:53]
	v_pk_fma_f32 v[54:55], v[148:149], v[198:199], v[54:55]
	v_pk_fma_f32 v[56:57], v[152:153], v[198:199], v[56:57]
	v_pk_fma_f32 v[50:51], v[172:173], v[198:199], v[50:51]
	v_fmac_f32_e32 v212, v164, v237
	v_fmac_f32_e32 v214, v164, v130
	v_fmac_f32_e32 v222, v152, v200
	v_fmac_f32_e32 v224, v152, v221
	v_pk_fma_f32 v[2:3], v[172:173], v[34:35], v[2:3]
	v_pk_fma_f32 v[36:37], v[144:145], v[34:35], v[36:37]
	v_pk_fma_f32 v[38:39], v[148:149], v[34:35], v[38:39]
	v_pk_fma_f32 v[40:41], v[152:153], v[34:35], v[40:41]
	v_pk_fma_f32 v[50:51], v[142:143], v[34:35], v[50:51]
	v_pk_fma_f32 v[52:53], v[146:147], v[34:35], v[52:53]
	v_pk_fma_f32 v[54:55], v[150:151], v[34:35], v[54:55]
	v_pk_fma_f32 v[56:57], v[154:155], v[34:35], v[56:57]
	v_fma_f32 v35, -v166, v130, v212
	v_fmac_f32_e32 v214, v166, v237
	v_fma_f32 v130, -v154, v221, v222
	v_fmac_f32_e32 v224, v154, v200
	v_pk_fma_f32 v[2:3], v[174:175], v[198:199], v[2:3]
	v_fmac_f32_e32 v215, v164, v35
	v_fmac_f32_e32 v217, v164, v214
	v_fmac_f32_e32 v225, v152, v130
	v_fmac_f32_e32 v227, v152, v224
	v_fma_f32 v202, -v166, v214, v215
	v_fmac_f32_e32 v217, v166, v35
	v_fma_f32 v203, -v154, v224, v225
	v_fmac_f32_e32 v227, v154, v130
	v_pk_fma_f32 v[36:37], v[182:183], v[198:199], v[36:37]
	v_fmac_f32_e32 v218, v164, v202
	v_fmac_f32_e32 v44, v164, v217
	v_fmac_f32_e32 v229, v152, v203
	v_fmac_f32_e32 v45, v152, v227
	v_pk_fma_f32 v[38:39], v[186:187], v[198:199], v[38:39]
	v_pk_fma_f32 v[40:41], v[178:179], v[198:199], v[40:41]
	v_cndmask_b32_e64 v198, v214, v213, s[6:7]
	v_cndmask_b32_e64 v199, v217, v216, s[6:7]
	v_fma_f32 v34, -v166, v217, v218
	v_cndmask_b32_e64 v200, v35, v233, s[6:7]
	v_cndmask_b32_e64 v201, v202, v235, s[6:7]
	v_fmac_f32_e32 v44, v166, v202
	v_fma_f32 v35, -v154, v227, v229
	v_fmac_f32_e32 v45, v154, v203
	v_cndmask_b32_e64 v202, v130, v234, s[6:7]
	v_cndmask_b32_e64 v203, v203, v236, s[6:7]
	v_cndmask_b32_e64 v204, v224, v223, s[6:7]
	v_cndmask_b32_e64 v205, v227, v226, s[6:7]
	v_pk_fma_f32 v[42:43], v[168:169], v[200:201], v[42:43]
	v_pk_fma_f32 v[26:27], v[168:169], v[198:199], v[26:27]
	v_pk_fma_f32 v[10:11], v[172:173], v[202:203], v[10:11]
	v_pk_fma_f32 v[58:59], v[172:173], v[204:205], v[58:59]
	v_pk_fma_f32 v[4:5], v[156:157], v[200:201], v[4:5]
	v_pk_fma_f32 v[6:7], v[156:157], v[198:199], v[6:7]
	v_pk_fma_f32 v[8:9], v[144:145], v[202:203], v[8:9]
	v_pk_fma_f32 v[12:13], v[144:145], v[204:205], v[12:13]
	v_pk_fma_f32 v[20:21], v[160:161], v[200:201], v[20:21]
	v_pk_fma_f32 v[22:23], v[160:161], v[198:199], v[22:23]
	v_pk_fma_f32 v[14:15], v[148:149], v[202:203], v[14:15]
	v_pk_fma_f32 v[24:25], v[148:149], v[204:205], v[24:25]
	v_pk_fma_f32 v[28:29], v[164:165], v[200:201], v[28:29]
	v_pk_fma_f32 v[30:31], v[164:165], v[198:199], v[30:31]
	v_pk_fma_f32 v[16:17], v[152:153], v[202:203], v[16:17]
	v_pk_fma_f32 v[32:33], v[152:153], v[204:205], v[32:33]
	v_pk_fma_f32 v[42:43], v[170:171], v[198:199], v[42:43]
	v_pk_fma_f32 v[26:27], v[140:141], v[200:201], v[26:27]
	v_pk_fma_f32 v[10:11], v[174:175], v[204:205], v[10:11]
	v_pk_fma_f32 v[58:59], v[142:143], v[202:203], v[58:59]
	v_pk_fma_f32 v[4:5], v[180:181], v[198:199], v[4:5]
	v_pk_fma_f32 v[6:7], v[158:159], v[200:201], v[6:7]
	v_pk_fma_f32 v[8:9], v[182:183], v[204:205], v[8:9]
	v_pk_fma_f32 v[12:13], v[146:147], v[202:203], v[12:13]
	v_pk_fma_f32 v[20:21], v[184:185], v[198:199], v[20:21]
	v_pk_fma_f32 v[22:23], v[162:163], v[200:201], v[22:23]
	v_pk_fma_f32 v[14:15], v[186:187], v[204:205], v[14:15]
	v_pk_fma_f32 v[24:25], v[150:151], v[202:203], v[24:25]
	v_pk_fma_f32 v[28:29], v[176:177], v[198:199], v[28:29]
	v_pk_fma_f32 v[30:31], v[166:167], v[200:201], v[30:31]
	v_pk_fma_f32 v[16:17], v[178:179], v[204:205], v[16:17]
	v_pk_fma_f32 v[32:33], v[154:155], v[202:203], v[32:33]
	v_cvt_pk_bf16_f32 v18, v60, v18
	v_cvt_pk_bf16_f32 v2, v2, v50
	v_cvt_pk_bf16_f32 v19, v61, v19
	ds_write2_b32 v129, v18, v2 offset1:32
	v_cvt_pk_bf16_f32 v2, v3, v51
	v_cvt_pk_bf16_f32 v48, v62, v48
	ds_write2_b32 v129, v19, v2 offset0:68 offset1:100
	v_cvt_pk_bf16_f32 v2, v36, v52
	v_cvt_pk_bf16_f32 v49, v63, v49
	ds_write2_b32 v129, v48, v2 offset0:136 offset1:168
	v_cvt_pk_bf16_f32 v2, v37, v53
	v_cvt_pk_bf16_f32 v60, v64, v194
	ds_write2_b32 v129, v49, v2 offset0:204 offset1:236
	v_cvt_pk_bf16_f32 v2, v38, v54
	v_add_u32_e32 v3, 0x800, v129
	v_cvt_pk_bf16_f32 v61, v65, v195
	ds_write2_b32 v3, v60, v2 offset0:32 offset1:64
	v_cvt_pk_bf16_f32 v2, v39, v55
	v_cvt_pk_bf16_f32 v46, v196, v46
	ds_write2_b32 v3, v61, v2 offset0:100 offset1:132
	v_cvt_pk_bf16_f32 v2, v40, v56
	v_cvt_pk_bf16_f32 v47, v197, v47
	ds_write2_b32 v3, v46, v2 offset0:168 offset1:200
	v_cvt_pk_bf16_f32 v2, v41, v57
	v_add_u32_e32 v3, 0xa00, v129
	v_cvt_pk_bf16_f32 v26, v42, v26
	ds_write2_b32 v3, v47, v2 offset0:108 offset1:140
	v_cvt_pk_bf16_f32 v2, v10, v58
	v_add_u32_e32 v3, 0x1000, v129
	v_cvt_pk_bf16_f32 v27, v43, v27
	ds_write2_b32 v3, v26, v2 offset0:64 offset1:96
	v_cvt_pk_bf16_f32 v2, v11, v59
	v_cvt_pk_bf16_f32 v4, v4, v6
	ds_write2_b32 v3, v27, v2 offset0:132 offset1:164
	v_cvt_pk_bf16_f32 v2, v8, v12
	v_cvt_pk_bf16_f32 v5, v5, v7
	ds_write2_b32 v3, v4, v2 offset0:200 offset1:232
	v_cvt_pk_bf16_f32 v2, v9, v13
	v_add_u32_e32 v3, 0x1400, v129
	v_cvt_pk_bf16_f32 v6, v20, v22
	ds_write2_b32 v3, v5, v2 offset0:12 offset1:44
	v_cvt_pk_bf16_f32 v2, v14, v24
	v_add_u32_e32 v3, 0x1800, v129
	v_cvt_pk_bf16_f32 v7, v21, v23
	ds_write2_b32 v3, v6, v2 offset0:96 offset1:128
	v_cvt_pk_bf16_f32 v2, v15, v25
	v_cvt_pk_bf16_f32 v20, v28, v30
	ds_write2_b32 v3, v7, v2 offset0:164 offset1:196
	v_cvt_pk_bf16_f32 v2, v16, v32
	v_add_u32_e32 v3, 0x1a00, v129
	v_cvt_pk_bf16_f32 v21, v29, v31
	ds_write2_b32 v3, v20, v2 offset0:104 offset1:136
	v_cvt_pk_bf16_f32 v2, v17, v33
	v_add_u32_e32 v3, 0x1c00, v129
	ds_write2_b32 v3, v21, v2 offset0:44 offset1:76
	ds_read_b128 v[2:5], v206
	ds_read_b128 v[18:21], v206 offset:32
	s_waitcnt lgkmcnt(1)
	v_mfma_f32_32x32x16_bf16 v[2:17], v[94:97], v[2:5], 0
	ds_read_b128 v[36:39], v206 offset:64
	ds_read_b128 v[40:43], v206 offset:96
	v_mov_b32_e32 v209, v45
	v_mov_b32_e32 v208, v35
	v_mov_b32_e32 v210, v44
	v_mov_b32_e32 v211, v34
	s_waitcnt lgkmcnt(2)
	v_mfma_f32_32x32x16_bf16 v[18:33], v[98:101], v[18:21], 0
	s_waitcnt lgkmcnt(1)
	v_mfma_f32_32x32x16_bf16 v[2:17], v[102:105], v[36:39], v[2:17]
	s_waitcnt lgkmcnt(0)
	v_mfma_f32_32x32x16_bf16 v[18:33], v[106:109], v[40:43], v[18:33]
	ds_read_b128 v[36:39], v206 offset:128
	ds_read_b128 v[40:43], v206 offset:160
	s_waitcnt lgkmcnt(1)
	v_mfma_f32_32x32x16_bf16 v[2:17], v[110:113], v[36:39], v[2:17]
	s_waitcnt lgkmcnt(0)
	v_mfma_f32_32x32x16_bf16 v[18:33], v[114:117], v[40:43], v[18:33]
	ds_read_b128 v[36:39], v206 offset:192
	ds_read_b128 v[40:43], v206 offset:224
	s_waitcnt lgkmcnt(1)
	v_mfma_f32_32x32x16_bf16 v[2:17], v[118:121], v[36:39], v[2:17]
	s_waitcnt lgkmcnt(0)
	v_mfma_f32_32x32x16_bf16 v[18:33], v[122:125], v[40:43], v[18:33]
	s_nop 9
	v_lshlrev_b32_e32 v10, 16, v90
	v_and_b32_e32 v11, 0xffff0000, v90
	v_lshlrev_b32_e32 v12, 16, v91
	v_and_b32_e32 v13, 0xffff0000, v91
	v_lshlrev_b32_e32 v14, 16, v92
	v_and_b32_e32 v15, 0xffff0000, v92
	v_lshlrev_b32_e32 v16, 16, v93
	v_pk_add_f32 v[2:3], v[2:3], v[18:19]
	v_pk_add_f32 v[4:5], v[4:5], v[20:21]
	v_pk_add_f32 v[8:9], v[8:9], v[24:25]
	v_pk_add_f32 v[6:7], v[6:7], v[22:23]
	v_pk_fma_f32 v[2:3], v[66:67], v[10:11], v[2:3]
	v_pk_fma_f32 v[4:5], v[68:69], v[12:13], v[4:5]
	v_and_b32_e32 v17, 0xffff0000, v93
	v_mul_f32_e32 v10, 0x3d372713, v2
	v_mul_f32_e32 v11, 0x3d372713, v3
	v_mul_f32_e32 v12, 0x3d372713, v4
	v_mul_f32_e32 v13, 0x3d372713, v5
	v_pk_fma_f32 v[6:7], v[70:71], v[14:15], v[6:7]
	v_pk_fma_f32 v[8:9], v[72:73], v[16:17], v[8:9]
	v_mul_f32_e32 v10, v2, v10
	v_mul_f32_e32 v11, v3, v11
	v_mul_f32_e32 v12, v4, v12
	v_mul_f32_e32 v13, v5, v13
	v_mul_f32_e32 v14, 0x3d372713, v6
	v_mul_f32_e32 v15, 0x3d372713, v7
	v_mul_f32_e32 v16, 0x3d372713, v8
	v_mul_f32_e32 v17, 0x3d372713, v9
	v_fma_f32 v10, v2, v10, v2
	v_fma_f32 v11, v3, v11, v3
	v_fma_f32 v12, v4, v12, v4
	v_fma_f32 v13, v5, v13, v5
	v_mul_f32_e32 v14, v6, v14
	v_mul_f32_e32 v15, v7, v15
	v_mul_f32_e32 v16, v8, v16
	v_mul_f32_e32 v17, v9, v17
	v_mul_f32_e32 v10, 0x3fcc422a, v10
	v_mul_f32_e32 v11, 0x3fcc422a, v11
	v_mul_f32_e32 v12, 0x3fcc422a, v12
	v_mul_f32_e32 v13, 0x3fcc422a, v13
	v_fma_f32 v14, v6, v14, v6
	v_fma_f32 v15, v7, v15, v7
	v_fma_f32 v16, v8, v16, v8
	v_fma_f32 v17, v9, v17, v9
	v_mul_f32_e32 v10, 0xbfb8aa3b, v10
	v_mul_f32_e32 v11, 0xbfb8aa3b, v11
	v_mul_f32_e32 v12, 0xbfb8aa3b, v12
	v_mul_f32_e32 v13, 0xbfb8aa3b, v13
	v_mul_f32_e32 v14, 0x3fcc422a, v14
	v_mul_f32_e32 v15, 0x3fcc422a, v15
	v_mul_f32_e32 v16, 0x3fcc422a, v16
	v_mul_f32_e32 v17, 0x3fcc422a, v17
	v_exp_f32_e32 v10, v10
	v_exp_f32_e32 v11, v11
	v_exp_f32_e32 v12, v12
	v_exp_f32_e32 v13, v13
	v_mul_f32_e32 v14, 0xbfb8aa3b, v14
	v_mul_f32_e32 v15, 0xbfb8aa3b, v15
	v_mul_f32_e32 v16, 0xbfb8aa3b, v16
	v_mul_f32_e32 v17, 0xbfb8aa3b, v17
	v_exp_f32_e32 v14, v14
	v_exp_f32_e32 v15, v15
	v_exp_f32_e32 v16, v16
	v_exp_f32_e32 v17, v17
	v_add_f32_e32 v10, 1.0, v10
	v_add_f32_e32 v11, 1.0, v11
	v_add_f32_e32 v12, 1.0, v12
	v_add_f32_e32 v13, 1.0, v13
	v_rcp_f32_e32 v10, v10
	v_rcp_f32_e32 v11, v11
	v_rcp_f32_e32 v12, v12
	v_rcp_f32_e32 v13, v13
	v_add_f32_e32 v14, 1.0, v14
	v_add_f32_e32 v15, 1.0, v15
	v_add_f32_e32 v16, 1.0, v16
	v_add_f32_e32 v17, 1.0, v17
	v_rcp_f32_e32 v14, v14
	v_rcp_f32_e32 v15, v15
	v_rcp_f32_e32 v16, v16
	v_rcp_f32_e32 v17, v17
	v_pk_mul_f32 v[2:3], v[2:3], v[10:11]
	v_pk_mul_f32 v[4:5], v[4:5], v[12:13]
	v_pk_mul_f32 v[6:7], v[6:7], v[14:15]
	v_pk_mul_f32 v[8:9], v[8:9], v[16:17]
	v_cvt_pk_bf16_f32 v2, v2, v3
	v_cvt_pk_bf16_f32 v3, v4, v5
	global_store_dwordx2 v[188:189], v[2:3], off
	v_cvt_pk_bf16_f32 v2, v6, v7
	v_cvt_pk_bf16_f32 v3, v8, v9
	global_store_dwordx2 v[188:189], v[2:3], off offset:16
	v_lshl_add_u64 v[188:189], v[188:189], 0, s[56:57]
	s_waitcnt vmcnt(10)
	s_cmp_eq_u32 s99, 1
	s_cbranch_scc1 .Ls5_cp1
	s_cmp_eq_u32 s99, 2
	s_cbranch_scc1 .Ls5_cp2
	v_mov_b64_e32 v[90:91], v[238:239]
	v_mov_b64_e32 v[92:93], v[240:241]
	s_mov_b32 s99, 1
	s_branch .Ls5_cpd
.Ls5_cp1:
	v_mov_b64_e32 v[90:91], v[242:243]
	v_mov_b64_e32 v[92:93], v[244:245]
	s_mov_b32 s99, 2
	s_branch .Ls5_cpd
.Ls5_cp2:
	v_mov_b64_e32 v[90:91], v[246:247]
	v_mov_b64_e32 v[92:93], v[248:249]
	s_mov_b32 s99, 0
.Ls5_cpd:
	s_cmp_ge_u32 s0, s40
	s_cbranch_scc1 .LBB0_353
.LBB0_351:
	s_add_i32 s0, s0, 1
	s_cmp_eq_u32 s99, 1
	s_cbranch_scc1 .Ls5_ld1
	s_cmp_eq_u32 s99, 2
	s_cbranch_scc1 .Ls5_ld2
	global_load_dwordx2 v[246:247], v[250:251], off
	global_load_dwordx2 v[248:249], v[250:251], off offset:16
	s_branch .Ls5_ldd
.Ls5_ld1:
	global_load_dwordx2 v[238:239], v[250:251], off
	global_load_dwordx2 v[240:241], v[250:251], off offset:16
	s_branch .Ls5_ldd
.Ls5_ld2:
	global_load_dwordx2 v[242:243], v[250:251], off
	global_load_dwordx2 v[244:245], v[250:251], off offset:16
.Ls5_ldd:
	v_lshl_add_u64 v[250:251], v[250:251], 0, s[56:57]
	s_branch .LBB0_350
.LBB0_353:
	s_waitcnt vmcnt(0)
	s_and_saveexec_b64 s[0:1], s[6:7]
	s_cbranch_execz .LBB0_344
	s_ashr_i32 s59, s58, 31
	s_lshl_b64 s[8:9], s[58:59], 8
	v_lshl_add_u64 v[2:3], v[138:139], 0, s[8:9]
	global_store_dword v[2:3], v34, off
	global_store_dword v[2:3], v35, off offset:128
	v_add_co_u32_e32 v2, vcc, 0x80000, v2
	s_nop 1
	v_addc_co_u32_e32 v3, vcc, 0, v3, vcc
	global_store_dword v[2:3], v44, off
	global_store_dword v[2:3], v45, off offset:128
	s_branch .LBB0_344

	.amdhsa_kernel _Z8yoco_fwd4Args
		.amdhsa_group_segment_fixed_size 0
		.amdhsa_private_segment_fixed_size 0
		.amdhsa_kernarg_size 480
		.amdhsa_user_sgpr_count 2
		.amdhsa_user_sgpr_dispatch_ptr 0
		.amdhsa_user_sgpr_queue_ptr 0
		.amdhsa_user_sgpr_kernarg_segment_ptr 1
		.amdhsa_user_sgpr_dispatch_id 0
		.amdhsa_user_sgpr_kernarg_preload_length 0
		.amdhsa_user_sgpr_kernarg_preload_offset 0
		.amdhsa_user_sgpr_private_segment_size 0
		.amdhsa_uses_dynamic_stack 0
		.amdhsa_enable_private_segment 0
		.amdhsa_system_sgpr_workgroup_id_x 1
		.amdhsa_system_sgpr_workgroup_id_y 0
		.amdhsa_system_sgpr_workgroup_id_z 0
		.amdhsa_system_sgpr_workgroup_info 0
		.amdhsa_system_vgpr_workitem_id 0
		.amdhsa_next_free_vgpr 256
		.amdhsa_next_free_sgpr 102
		.amdhsa_accum_offset 256
		.amdhsa_reserve_vcc 1
		.amdhsa_float_round_mode_32 0
		.amdhsa_float_round_mode_16_64 0
		.amdhsa_float_denorm_mode_32 3
		.amdhsa_float_denorm_mode_16_64 3
		.amdhsa_dx10_clamp 1
		.amdhsa_ieee_mode 1
		.amdhsa_fp16_overflow 0
		.amdhsa_tg_split 0
		.amdhsa_exception_fp_ieee_invalid_op 0
		.amdhsa_exception_fp_denorm_src 0
		.amdhsa_exception_fp_ieee_div_zero 0
		.amdhsa_exception_fp_ieee_overflow 0
		.amdhsa_exception_fp_ieee_underflow 0
		.amdhsa_exception_fp_ieee_inexact 0
		.amdhsa_exception_int_div_zero 0
	.end_amdhsa_kernel

amdhsa.kernels:
  - .agpr_count:     0
    .args:
      - .offset:         0
        .size:           224
        .value_kind:     by_value
      - .offset:         224
        .size:           4
        .value_kind:     hidden_block_count_x
      - .offset:         228
        .size:           4
        .value_kind:     hidden_block_count_y
      - .offset:         232
        .size:           4
        .value_kind:     hidden_block_count_z
      - .offset:         236
        .size:           2
        .value_kind:     hidden_group_size_x
      - .offset:         238
        .size:           2
        .value_kind:     hidden_group_size_y
      - .offset:         240
        .size:           2
        .value_kind:     hidden_group_size_z
      - .offset:         242
        .size:           2
        .value_kind:     hidden_remainder_x
      - .offset:         244
        .size:           2
        .value_kind:     hidden_remainder_y
      - .offset:         246
        .size:           2
        .value_kind:     hidden_remainder_z
      - .offset:         264
        .size:           8
        .value_kind:     hidden_global_offset_x
      - .offset:         272
        .size:           8
        .value_kind:     hidden_global_offset_y
      - .offset:         280
        .size:           8
        .value_kind:     hidden_global_offset_z
      - .offset:         288
        .size:           2
        .value_kind:     hidden_grid_dims
      - .offset:         344
        .size:           4
        .value_kind:     hidden_dynamic_lds_size
    .group_segment_fixed_size: 0
    .kernarg_segment_align: 8
    .kernarg_segment_size: 480
    .language:       OpenCL C
    .language_version:
      - 2
      - 0
    .max_flat_workgroup_size: 512
    .name:           _Z8yoco_fwd4Args
    .private_segment_fixed_size: 0
    .sgpr_count:     108
    .sgpr_spill_count: 26
    .symbol:         _Z8yoco_fwd4Args.kd
    .uniform_work_group_size: 1
    .uses_dynamic_stack: false
    .vgpr_count:     256
    .vgpr_spill_count: 0
    .wavefront_size: 64
